# HGRN stage C: conditional score MFMAs accumulate in place (sc0 v[16:31], sc1 v[32:47]) on scalar branches, compiler PHI register copies and dead zero-init removed, fragment reads double-buffered
# speedup vs baseline: 1.0060x; 1.0060x over previous
; DI bf16_t f2bf(float x) { return (bf16_t)(pk2(x, 0.f) & 0xffffu); }
; DI void hgrn_stageC(const Params& p, const int j_even, char* lds) {
;     ...
;     __syncthreads();
;     const int k = tid & 127, seg = tid >> 7;
;     float lv[16], bv[16];
;     float run = 0.f;
; #pragma unroll
;     for (int i = 0; i < 16; ++i) { lv[i] = lfT[(seg * 16 + i) * 128 + k]; run += lv[i]; bv[i] = run; }
;     part[seg * 128 + k] = run;
;     __syncthreads();
;     {
;       const float p0 = part[k], p1 = part[128 + k], p2 = part[256 + k];
;       const float pre = (seg > 0 ? p0 : 0.f) + (seg > 1 ? p1 : 0.f) + (seg > 2 ? p2 : 0.f);
;       const float bmid = p0 + p1;
; #pragma unroll
;       for (int i = 0; i < 16; ++i) {
;         const int t = seg * 16 + i;
;         const float bt = pre + bv[i];
;         const float qv = qcur[i];
;         const float kk = 1.f - __expf(lv[i]);
;         *(bf16_t*)(Q1 + t * QROW + k * 2) = f2bf(qv * __expf(bt));
;         *(bf16_t*)(Q2 + t * QROW + k * 2) = f2bf(qv * __expf(fminf(bt - bmid, 80.f)));
;         *(bf16_t*)(K2 + t * QROW + k * 2) = f2bf(kk * __expf(fminf(bmid - bt, 80.f)));
;       }
.LBB0_595:
	s_waitcnt lgkmcnt(0)
	s_barrier
	ds_read2st64_b32 v[34:35], v163 offset1:2
	v_lshlrev_b32_e32 v50, 16, v28
	v_lshlrev_b32_e32 v51, 16, v29
	ds_read2st64_b32 v[28:29], v163 offset0:4 offset1:6
	ds_read2st64_b32 v[36:37], v163 offset0:8 offset1:10
	s_waitcnt lgkmcnt(2)
	v_add_f32_e32 v0, 0, v34
	v_add_f32_e32 v52, v0, v35
	ds_read2st64_b32 v[38:39], v163 offset0:12 offset1:14
	s_waitcnt lgkmcnt(2)
	v_add_f32_e32 v53, v52, v28
	v_lshlrev_b32_e32 v48, 16, v24
	v_lshlrev_b32_e32 v49, 16, v25
	v_add_f32_e32 v54, v53, v29
	ds_read2st64_b32 v[24:25], v163 offset0:16 offset1:18
	s_waitcnt lgkmcnt(2)
	v_add_f32_e32 v55, v54, v36
	v_lshlrev_b32_e32 v46, 16, v22
	v_lshlrev_b32_e32 v47, 16, v23
	v_add_f32_e32 v56, v55, v37
	ds_read2st64_b32 v[22:23], v163 offset0:20 offset1:22
	s_waitcnt lgkmcnt(2)
	v_add_f32_e32 v57, v56, v38
	v_lshlrev_b32_e32 v44, 16, v20
	v_lshlrev_b32_e32 v45, 16, v21
	v_add_f32_e32 v58, v57, v39
	ds_read2st64_b32 v[20:21], v163 offset0:24 offset1:26
	s_waitcnt lgkmcnt(2)
	v_add_f32_e32 v59, v58, v24
	v_lshlrev_b32_e32 v42, 16, v18
	v_lshlrev_b32_e32 v43, 16, v19
	v_add_f32_e32 v60, v59, v25
	ds_read2st64_b32 v[18:19], v163 offset0:28 offset1:30
	s_waitcnt lgkmcnt(2)
	v_add_f32_e32 v61, v60, v22
	v_add_f32_e32 v62, v61, v23
	s_waitcnt lgkmcnt(1)
	v_add_f32_e32 v63, v62, v20
	v_add_f32_e32 v64, v63, v21
	s_waitcnt lgkmcnt(0)
	v_add_f32_e32 v65, v64, v18
	v_add_f32_e32 v66, v65, v19
	ds_write_b32 v164, v66
	s_waitcnt lgkmcnt(0)
	s_barrier
	ds_read2st64_b32 v[40:41], v165 offset1:2
	ds_read_b32 v67, v165 offset:1024
	v_mul_f32_e32 v35, 0x3fb8aa3b, v35
	v_exp_f32_e32 v35, v35
	v_mul_f32_e32 v28, 0x3fb8aa3b, v28
	s_waitcnt lgkmcnt(1)
	v_cndmask_b32_e64 v68, 0, v40, s[6:7]
	v_cndmask_b32_e64 v69, 0, v41, s[8:9]
	v_add_f32_e32 v68, v68, v69
	s_waitcnt lgkmcnt(0)
	v_cndmask_b32_e64 v67, 0, v67, s[10:11]
	v_add_f32_e32 v67, v68, v67
	v_add_f32_e32 v68, v0, v67
	v_mul_f32_e32 v0, 0x3fb8aa3b, v34
	v_exp_f32_e32 v34, v0
	v_mul_f32_e32 v0, 0x3fb8aa3b, v68
	v_exp_f32_e32 v69, v0
	v_add_f32_e32 v40, v40, v41
	v_sub_f32_e32 v34, 1.0, v34
	v_exp_f32_e32 v28, v28
	v_mul_f32_e32 v41, v69, v42
	v_cvt_pk_bf16_f32 v41, v41, s0
	ds_write_b16 v172, v41 offset:34816
	v_sub_f32_e32 v41, v68, v40
	v_min_f32_e32 v41, 0x42a00000, v41
	v_mul_f32_e32 v41, 0x3fb8aa3b, v41
	v_exp_f32_e32 v41, v41
	v_sub_f32_e32 v68, v40, v68
	v_min_f32_e32 v68, 0x42a00000, v68
	v_mul_f32_e32 v68, 0x3fb8aa3b, v68
	v_mul_f32_e32 v41, v41, v42
	v_cvt_pk_bf16_f32 v41, v41, s0
	v_exp_f32_e32 v68, v68
	ds_write_b16 v172, v41 offset:52224
	v_add_f32_e32 v41, v52, v67
	v_mul_f32_e32 v42, 0x3fb8aa3b, v41
	v_exp_f32_e32 v42, v42
	v_mul_f32_e32 v34, v34, v68
	v_cvt_pk_bf16_f32 v34, v34, s0
	ds_write_b16 v173, v34
	v_sub_f32_e32 v34, 1.0, v35
	v_mul_f32_e32 v35, v42, v43
	v_cvt_pk_bf16_f32 v35, v35, s0
	ds_write_b16 v172, v35 offset:35088
	v_sub_f32_e32 v35, v41, v40
	v_min_f32_e32 v35, 0x42a00000, v35
	v_mul_f32_e32 v35, 0x3fb8aa3b, v35
	v_exp_f32_e32 v35, v35
	v_sub_f32_e32 v41, v40, v41
	v_min_f32_e32 v41, 0x42a00000, v41
	v_mul_f32_e32 v41, 0x3fb8aa3b, v41
	v_exp_f32_e32 v41, v41
	v_mul_f32_e32 v35, v35, v43
	v_cvt_pk_bf16_f32 v35, v35, s0
	ds_write_b16 v172, v35 offset:52496
	v_add_f32_e32 v35, v53, v67
	v_mul_f32_e32 v34, v34, v41
	v_mul_f32_e32 v41, 0x3fb8aa3b, v35
	v_exp_f32_e32 v41, v41
	v_cvt_pk_bf16_f32 v34, v34, s0
	ds_write_b16 v173, v34 offset:272
	v_sub_f32_e32 v28, 1.0, v28
	v_mul_f32_e32 v34, v41, v44
	v_cvt_pk_bf16_f32 v34, v34, s0
	ds_write_b16 v172, v34 offset:35360
	v_sub_f32_e32 v34, v35, v40
	v_min_f32_e32 v34, 0x42a00000, v34
	v_mul_f32_e32 v34, 0x3fb8aa3b, v34
	v_exp_f32_e32 v34, v34
	v_sub_f32_e32 v35, v40, v35
	v_min_f32_e32 v35, 0x42a00000, v35
	v_mul_f32_e32 v35, 0x3fb8aa3b, v35
	v_exp_f32_e32 v35, v35
	v_mul_f32_e32 v34, v34, v44
	v_cvt_pk_bf16_f32 v34, v34, s0
	ds_write_b16 v172, v34 offset:52768
	v_add_f32_e32 v34, v54, v67
	v_mul_f32_e32 v28, v28, v35
	v_mul_f32_e32 v29, 0x3fb8aa3b, v29
	v_mul_f32_e32 v35, 0x3fb8aa3b, v34
	v_exp_f32_e32 v29, v29
	v_exp_f32_e32 v35, v35
	v_cvt_pk_bf16_f32 v28, v28, s0
	ds_write_b16 v173, v28 offset:544
	v_sub_f32_e32 v28, 1.0, v29
	v_mul_f32_e32 v29, v35, v45
	v_cvt_pk_bf16_f32 v29, v29, s0
	ds_write_b16 v172, v29 offset:35632
	v_sub_f32_e32 v29, v34, v40
	v_min_f32_e32 v29, 0x42a00000, v29
	v_mul_f32_e32 v29, 0x3fb8aa3b, v29
	v_exp_f32_e32 v29, v29
	v_sub_f32_e32 v34, v40, v34
	v_min_f32_e32 v34, 0x42a00000, v34
	v_mul_f32_e32 v34, 0x3fb8aa3b, v34
	v_exp_f32_e32 v34, v34
	v_mul_f32_e32 v29, v29, v45
	v_cvt_pk_bf16_f32 v29, v29, s0
	ds_write_b16 v172, v29 offset:53040
	v_add_f32_e32 v29, v55, v67
	v_mul_f32_e32 v28, v28, v34
	v_mul_f32_e32 v34, 0x3fb8aa3b, v36
	v_mul_f32_e32 v35, 0x3fb8aa3b, v29
	v_exp_f32_e32 v34, v34
	v_exp_f32_e32 v35, v35
	v_cvt_pk_bf16_f32 v28, v28, s0
	ds_write_b16 v173, v28 offset:816
	v_sub_f32_e32 v28, 1.0, v34
	v_mul_f32_e32 v34, v35, v46
	v_cvt_pk_bf16_f32 v34, v34, s0
	ds_write_b16 v172, v34 offset:35904
	v_sub_f32_e32 v34, v29, v40
	v_min_f32_e32 v34, 0x42a00000, v34
	v_sub_f32_e32 v29, v40, v29
	v_mul_f32_e32 v34, 0x3fb8aa3b, v34
	v_min_f32_e32 v29, 0x42a00000, v29
	v_exp_f32_e32 v34, v34
	v_mul_f32_e32 v29, 0x3fb8aa3b, v29
	v_exp_f32_e32 v29, v29
	v_lshlrev_b32_e32 v26, 16, v26
	v_mul_f32_e32 v34, v34, v46
	v_cvt_pk_bf16_f32 v34, v34, s0
	v_mul_f32_e32 v28, v28, v29
	v_add_f32_e32 v29, v56, v67
	ds_write_b16 v172, v34 offset:53312
	v_mul_f32_e32 v34, 0x3fb8aa3b, v37
	v_mul_f32_e32 v35, 0x3fb8aa3b, v29
	v_exp_f32_e32 v34, v34
	v_exp_f32_e32 v35, v35
	v_cvt_pk_bf16_f32 v28, v28, s0
	ds_write_b16 v173, v28 offset:1088
	v_sub_f32_e32 v28, 1.0, v34
	v_mul_f32_e32 v34, v35, v47
; DI bf16_t f2bf(float x) { return (bf16_t)(pk2(x, 0.f) & 0xffffu); }
; DI void hgrn_stageC(const Params& p, const int j_even, char* lds) {
;     ...
; #pragma unroll
;       for (int i = 0; i < 16; ++i) {
;         const int t = seg * 16 + i;
;         const float bt = pre + bv[i];
;         const float qv = qcur[i];
;         const float kk = 1.f - __expf(lv[i]);
;         *(bf16_t*)(Q1 + t * QROW + k * 2) = f2bf(qv * __expf(bt));
;         *(bf16_t*)(Q2 + t * QROW + k * 2) = f2bf(qv * __expf(fminf(bt - bmid, 80.f)));
;         *(bf16_t*)(K2 + t * QROW + k * 2) = f2bf(kk * __expf(fminf(bmid - bt, 80.f)));
;       }
	v_cvt_pk_bf16_f32 v34, v34, s0
	ds_write_b16 v172, v34 offset:36176
	v_sub_f32_e32 v34, v29, v40
	v_min_f32_e32 v34, 0x42a00000, v34
	v_sub_f32_e32 v29, v40, v29
	v_mul_f32_e32 v34, 0x3fb8aa3b, v34
	v_min_f32_e32 v29, 0x42a00000, v29
	v_exp_f32_e32 v34, v34
	v_mul_f32_e32 v29, 0x3fb8aa3b, v29
	v_exp_f32_e32 v29, v29
	v_mul_f32_e32 v24, 0x3fb8aa3b, v24
	v_mul_f32_e32 v34, v34, v47
	v_cvt_pk_bf16_f32 v34, v34, s0
	v_mul_f32_e32 v28, v28, v29
	v_add_f32_e32 v29, v57, v67
	ds_write_b16 v172, v34 offset:53584
	v_mul_f32_e32 v34, 0x3fb8aa3b, v38
	v_mul_f32_e32 v35, 0x3fb8aa3b, v29
	v_exp_f32_e32 v34, v34
	v_exp_f32_e32 v35, v35
	v_cvt_pk_bf16_f32 v28, v28, s0
	ds_write_b16 v173, v28 offset:1360
	v_sub_f32_e32 v28, 1.0, v34
	v_mul_f32_e32 v34, v35, v48
	v_cvt_pk_bf16_f32 v34, v34, s0
	ds_write_b16 v172, v34 offset:36448
	v_sub_f32_e32 v34, v29, v40
	v_min_f32_e32 v34, 0x42a00000, v34
	v_sub_f32_e32 v29, v40, v29
	v_mul_f32_e32 v34, 0x3fb8aa3b, v34
	v_min_f32_e32 v29, 0x42a00000, v29
	v_exp_f32_e32 v34, v34
	v_mul_f32_e32 v29, 0x3fb8aa3b, v29
	v_exp_f32_e32 v29, v29
	v_exp_f32_e32 v24, v24
	v_mul_f32_e32 v34, v34, v48
	v_cvt_pk_bf16_f32 v34, v34, s0
	v_mul_f32_e32 v28, v28, v29
	v_add_f32_e32 v29, v58, v67
	ds_write_b16 v172, v34 offset:53856
	v_mul_f32_e32 v34, 0x3fb8aa3b, v39
	v_mul_f32_e32 v35, 0x3fb8aa3b, v29
	v_exp_f32_e32 v34, v34
	v_exp_f32_e32 v35, v35
	v_cvt_pk_bf16_f32 v28, v28, s0
	ds_write_b16 v173, v28 offset:1632
	v_sub_f32_e32 v28, 1.0, v34
	v_mul_f32_e32 v34, v35, v49
	v_cvt_pk_bf16_f32 v34, v34, s0
	ds_write_b16 v172, v34 offset:36720
	v_sub_f32_e32 v34, v29, v40
	v_min_f32_e32 v34, 0x42a00000, v34
	v_sub_f32_e32 v29, v40, v29
	v_mul_f32_e32 v34, 0x3fb8aa3b, v34
	v_min_f32_e32 v29, 0x42a00000, v29
	v_exp_f32_e32 v34, v34
	v_mul_f32_e32 v29, 0x3fb8aa3b, v29
	v_exp_f32_e32 v29, v29
	v_mul_f32_e32 v25, 0x3fb8aa3b, v25
	v_mul_f32_e32 v34, v34, v49
	v_cvt_pk_bf16_f32 v34, v34, s0
	v_mul_f32_e32 v28, v28, v29
	v_add_f32_e32 v29, v59, v67
	ds_write_b16 v172, v34 offset:54128
	v_mul_f32_e32 v34, 0x3fb8aa3b, v29
	v_exp_f32_e32 v34, v34
	v_cvt_pk_bf16_f32 v28, v28, s0
	ds_write_b16 v173, v28 offset:1904
	v_exp_f32_e32 v25, v25
	v_mul_f32_e32 v28, v34, v26
	v_cvt_pk_bf16_f32 v28, v28, s0
	ds_write_b16 v172, v28 offset:36992
	v_sub_f32_e32 v28, v29, v40
	v_min_f32_e32 v28, 0x42a00000, v28
	v_mul_f32_e32 v28, 0x3fb8aa3b, v28
	v_exp_f32_e32 v28, v28
	v_sub_f32_e32 v29, v40, v29
	v_min_f32_e32 v29, 0x42a00000, v29
	v_mul_f32_e32 v29, 0x3fb8aa3b, v29
	v_mul_f32_e32 v26, v28, v26
	v_cvt_pk_bf16_f32 v26, v26, s0
	v_exp_f32_e32 v29, v29
	ds_write_b16 v172, v26 offset:54400
	v_add_f32_e32 v26, v60, v67
	v_mul_f32_e32 v28, 0x3fb8aa3b, v26
	v_exp_f32_e32 v28, v28
	v_sub_f32_e32 v24, 1.0, v24
	v_mul_f32_e32 v24, v24, v29
	v_cvt_pk_bf16_f32 v24, v24, s0
	ds_write_b16 v173, v24 offset:2176
	v_sub_f32_e32 v24, 1.0, v25
	v_mul_f32_e32 v25, v28, v50
	v_cvt_pk_bf16_f32 v25, v25, s0
	ds_write_b16 v172, v25 offset:37264
	v_sub_f32_e32 v25, v26, v40
	v_min_f32_e32 v25, 0x42a00000, v25
	v_mul_f32_e32 v25, 0x3fb8aa3b, v25
	v_exp_f32_e32 v25, v25
	v_sub_f32_e32 v26, v40, v26
	v_min_f32_e32 v26, 0x42a00000, v26
	v_mul_f32_e32 v26, 0x3fb8aa3b, v26
	v_exp_f32_e32 v26, v26
	v_mul_f32_e32 v25, v25, v50
	v_cvt_pk_bf16_f32 v25, v25, s0
	ds_write_b16 v172, v25 offset:54672
	v_add_f32_e32 v25, v61, v67
	v_mul_f32_e32 v24, v24, v26
	v_mul_f32_e32 v26, 0x3fb8aa3b, v25
	v_exp_f32_e32 v26, v26
	v_cvt_pk_bf16_f32 v24, v24, s0
	ds_write_b16 v173, v24 offset:2448
	v_mul_f32_e32 v22, 0x3fb8aa3b, v22
	v_mul_f32_e32 v24, v26, v51
	v_cvt_pk_bf16_f32 v24, v24, s0
	ds_write_b16 v172, v24 offset:37536
	v_sub_f32_e32 v24, v25, v40
	v_min_f32_e32 v24, 0x42a00000, v24
	v_mul_f32_e32 v24, 0x3fb8aa3b, v24
	v_exp_f32_e32 v24, v24
	v_sub_f32_e32 v25, v40, v25
	v_min_f32_e32 v25, 0x42a00000, v25
	v_exp_f32_e32 v22, v22
	v_mul_f32_e32 v25, 0x3fb8aa3b, v25
	v_exp_f32_e32 v25, v25
	v_mul_f32_e32 v24, v24, v51
	v_cvt_pk_bf16_f32 v24, v24, s0
	v_sub_f32_e32 v22, 1.0, v22
	ds_write_b16 v172, v24 offset:54944
	v_add_f32_e32 v24, v62, v67
	v_mul_f32_e32 v22, v22, v25
	v_mul_f32_e32 v23, 0x3fb8aa3b, v23
	v_mul_f32_e32 v25, 0x3fb8aa3b, v24
	v_exp_f32_e32 v23, v23
	v_exp_f32_e32 v25, v25
	v_lshlrev_b32_e32 v31, 16, v31
	v_cvt_pk_bf16_f32 v22, v22, s0
	ds_write_b16 v173, v22 offset:2720
	v_sub_f32_e32 v22, 1.0, v23
	v_mul_f32_e32 v23, v25, v31
	v_cvt_pk_bf16_f32 v23, v23, s0
	ds_write_b16 v172, v23 offset:37808
	v_sub_f32_e32 v23, v24, v40
	v_min_f32_e32 v23, 0x42a00000, v23
	v_mul_f32_e32 v23, 0x3fb8aa3b, v23
	v_exp_f32_e32 v23, v23
	v_sub_f32_e32 v24, v40, v24
	v_min_f32_e32 v24, 0x42a00000, v24
	v_mul_f32_e32 v24, 0x3fb8aa3b, v24
	v_exp_f32_e32 v24, v24
	v_mul_f32_e32 v23, v23, v31
	v_cvt_pk_bf16_f32 v23, v23, s0
	ds_write_b16 v172, v23 offset:55216
	v_add_f32_e32 v23, v63, v67
	v_mul_f32_e32 v22, v22, v24
	v_mul_f32_e32 v24, 0x3fb8aa3b, v23
	v_exp_f32_e32 v24, v24
	v_lshlrev_b32_e32 v32, 16, v32
	v_cvt_pk_bf16_f32 v22, v22, s0
	ds_write_b16 v173, v22 offset:2992
	v_mul_f32_e32 v22, v24, v32
	v_cvt_pk_bf16_f32 v22, v22, s0
	ds_write_b16 v172, v22 offset:38080
	v_sub_f32_e32 v22, v23, v40
	v_min_f32_e32 v22, 0x42a00000, v22
	v_mul_f32_e32 v22, 0x3fb8aa3b, v22
	v_exp_f32_e32 v22, v22
	v_sub_f32_e32 v23, v40, v23
	v_mul_f32_e32 v20, 0x3fb8aa3b, v20
	v_min_f32_e32 v23, 0x42a00000, v23
	v_exp_f32_e32 v20, v20
	v_mul_f32_e32 v23, 0x3fb8aa3b, v23
	v_exp_f32_e32 v23, v23
	v_mul_f32_e32 v22, v22, v32
	v_cvt_pk_bf16_f32 v22, v22, s0
	v_sub_f32_e32 v20, 1.0, v20
	ds_write_b16 v172, v22 offset:55488
	v_add_f32_e32 v22, v64, v67
	v_mul_f32_e32 v20, v20, v23
	v_mul_f32_e32 v21, 0x3fb8aa3b, v21
; #define MFMA32(a, b, c) __builtin_amdgcn_mfma_f32_32x32x16_bf16((a), (b), (c), 0, 0, 0)
; DI void hgrn_stageC(const Params& p, const int j_even, char* lds) {
;     ...
; #pragma unroll
;     for (int i = 0; i < 4; ++i) { const int idx = tid + 512 * i, row = idx >> 4, ch = idx & 15; *(u32x4*)(ST + row * QROW + ch * 16) = sreg[i]; }
;     __syncthreads();
;     {
;       const int vt = wave & 3, tt = wave >> 2;
;       const int t = tt * 32 + r;
;       f32x16 sc[2];
; #pragma unroll
;       for (int st = 0; st < 2; ++st)
; #pragma unroll
;         for (int i = 0; i < 16; ++i) sc[st][i] = 0.f;
; #pragma unroll
;       for (int ks = 0; ks < 8; ++ks) {
;         bf16x8 qb = *(const bf16x8*)(Q2 + t * QROW + ks * 32 + hh * 16);
; #pragma unroll
;         for (int st = 0; st < 2; ++st) {
;           if (st <= tt) {
;             bf16x8 a = *(const bf16x8*)(K2 + (st * 32 + r) * QROW + ks * 32 + hh * 16);
;             sc[st] = MFMA32(a, qb, sc[st]);
;           }
;         }
;       }
	v_mul_f32_e32 v23, 0x3fb8aa3b, v22
	v_exp_f32_e32 v21, v21
	v_exp_f32_e32 v23, v23
	v_lshlrev_b32_e32 v27, 16, v27
	v_cvt_pk_bf16_f32 v20, v20, s0
	ds_write_b16 v173, v20 offset:3264
	v_sub_f32_e32 v20, 1.0, v21
	v_mul_f32_e32 v21, v23, v27
	v_cvt_pk_bf16_f32 v21, v21, s0
	ds_write_b16 v172, v21 offset:38352
	v_sub_f32_e32 v21, v22, v40
	v_min_f32_e32 v21, 0x42a00000, v21
	v_mul_f32_e32 v21, 0x3fb8aa3b, v21
	v_exp_f32_e32 v21, v21
	v_sub_f32_e32 v22, v40, v22
	v_min_f32_e32 v22, 0x42a00000, v22
	v_mul_f32_e32 v22, 0x3fb8aa3b, v22
	v_exp_f32_e32 v22, v22
	v_mul_f32_e32 v21, v21, v27
	v_cvt_pk_bf16_f32 v21, v21, s0
	ds_write_b16 v172, v21 offset:55760
	v_add_f32_e32 v21, v65, v67
	v_mul_f32_e32 v20, v20, v22
	v_mul_f32_e32 v22, 0x3fb8aa3b, v21
	v_exp_f32_e32 v22, v22
	v_lshlrev_b32_e32 v30, 16, v30
	v_cvt_pk_bf16_f32 v20, v20, s0
	ds_write_b16 v173, v20 offset:3536
	v_mul_f32_e32 v20, v22, v30
	v_cvt_pk_bf16_f32 v20, v20, s0
	ds_write_b16 v172, v20 offset:38624
	v_sub_f32_e32 v20, v21, v40
	v_min_f32_e32 v20, 0x42a00000, v20
	v_mul_f32_e32 v20, 0x3fb8aa3b, v20
	v_exp_f32_e32 v20, v20
	v_sub_f32_e32 v21, v40, v21
	v_mul_f32_e32 v18, 0x3fb8aa3b, v18
	v_min_f32_e32 v21, 0x42a00000, v21
	v_exp_f32_e32 v18, v18
	v_mul_f32_e32 v21, 0x3fb8aa3b, v21
	v_exp_f32_e32 v21, v21
	v_mul_f32_e32 v20, v20, v30
	v_cvt_pk_bf16_f32 v20, v20, s0
	v_sub_f32_e32 v18, 1.0, v18
	ds_write_b16 v172, v20 offset:56032
	v_add_f32_e32 v20, v66, v67
	v_mul_f32_e32 v18, v18, v21
	v_mul_f32_e32 v19, 0x3fb8aa3b, v19
	v_mul_f32_e32 v21, 0x3fb8aa3b, v20
	v_exp_f32_e32 v19, v19
	v_exp_f32_e32 v21, v21
	v_lshlrev_b32_e32 v33, 16, v33
	v_cvt_pk_bf16_f32 v18, v18, s0
	ds_write_b16 v173, v18 offset:3808
	v_sub_f32_e32 v18, 1.0, v19
	v_mul_f32_e32 v19, v21, v33
	v_cvt_pk_bf16_f32 v19, v19, s0
	ds_write_b16 v172, v19 offset:38896
	v_sub_f32_e32 v19, v20, v40
	v_sub_f32_e32 v20, v40, v20
	v_min_f32_e32 v19, 0x42a00000, v19
	v_min_f32_e32 v20, 0x42a00000, v20
	v_mul_f32_e32 v19, 0x3fb8aa3b, v19
	v_mul_f32_e32 v20, 0x3fb8aa3b, v20
	v_exp_f32_e32 v19, v19
	v_exp_f32_e32 v20, v20
	v_mov_b32_e32 v0, 0
	v_mov_b32_e32 v48, 0
	v_mul_f32_e32 v19, v19, v33
	v_mul_f32_e32 v18, v18, v20
	v_cvt_pk_bf16_f32 v19, v19, s0
	v_cvt_pk_bf16_f32 v18, v18, s0
	ds_write_b16 v172, v19 offset:56304
	ds_write_b16 v173, v18 offset:4080
	s_waitcnt vmcnt(3)
	ds_write_b128 v174, v[2:5]
	s_waitcnt vmcnt(2)
	ds_write_b128 v175, v[6:9]
	s_waitcnt vmcnt(1)
	ds_write_b128 v176, v[10:13]
	s_waitcnt vmcnt(0)
	ds_write_b128 v177, v[14:17]
	s_waitcnt lgkmcnt(0)
	s_barrier
	s_and_b64 vcc, exec, s[16:17]
	s_cbranch_vccz .Lstc_lo
	ds_read_b128 v[2:5], v179 offset:52224
	ds_read_b128 v[6:9], v180
	ds_read_b128 v[10:13], v180 offset:8704
	ds_read_b128 v[64:67], v179 offset:52256
	ds_read_b128 v[68:71], v180 offset:32
	ds_read_b128 v[72:75], v180 offset:8736
	s_waitcnt lgkmcnt(3)
	v_mfma_f32_32x32x16_bf16 v[16:31], v[6:9], v[2:5], 0
	v_mfma_f32_32x32x16_bf16 v[32:47], v[10:13], v[2:5], 0
	ds_read_b128 v[2:5], v179 offset:52288
	ds_read_b128 v[6:9], v180 offset:64
	ds_read_b128 v[10:13], v180 offset:8768
	s_waitcnt lgkmcnt(3)
	v_mfma_f32_32x32x16_bf16 v[16:31], v[68:71], v[64:67], v[16:31]
	v_mfma_f32_32x32x16_bf16 v[32:47], v[72:75], v[64:67], v[32:47]
	ds_read_b128 v[64:67], v179 offset:52320
	ds_read_b128 v[68:71], v180 offset:96
	ds_read_b128 v[72:75], v180 offset:8800
	s_waitcnt lgkmcnt(3)
	v_mfma_f32_32x32x16_bf16 v[16:31], v[6:9], v[2:5], v[16:31]
	v_mfma_f32_32x32x16_bf16 v[32:47], v[10:13], v[2:5], v[32:47]
	ds_read_b128 v[2:5], v179 offset:52352
	ds_read_b128 v[6:9], v180 offset:128
	ds_read_b128 v[10:13], v180 offset:8832
	s_waitcnt lgkmcnt(3)
	v_mfma_f32_32x32x16_bf16 v[16:31], v[68:71], v[64:67], v[16:31]
	v_mfma_f32_32x32x16_bf16 v[32:47], v[72:75], v[64:67], v[32:47]
	ds_read_b128 v[64:67], v179 offset:52384
	ds_read_b128 v[68:71], v180 offset:160
	ds_read_b128 v[72:75], v180 offset:8864
	s_waitcnt lgkmcnt(3)
	v_mfma_f32_32x32x16_bf16 v[16:31], v[6:9], v[2:5], v[16:31]
	v_mfma_f32_32x32x16_bf16 v[32:47], v[10:13], v[2:5], v[32:47]
	ds_read_b128 v[2:5], v179 offset:52416
	ds_read_b128 v[6:9], v180 offset:192
	ds_read_b128 v[10:13], v180 offset:8896
	s_waitcnt lgkmcnt(3)
	v_mfma_f32_32x32x16_bf16 v[16:31], v[68:71], v[64:67], v[16:31]
	v_mfma_f32_32x32x16_bf16 v[32:47], v[72:75], v[64:67], v[32:47]
	ds_read_b128 v[64:67], v179 offset:52448
	ds_read_b128 v[68:71], v180 offset:224
	ds_read_b128 v[72:75], v180 offset:8928
	s_waitcnt lgkmcnt(3)
	v_mfma_f32_32x32x16_bf16 v[16:31], v[6:9], v[2:5], v[16:31]
	v_mfma_f32_32x32x16_bf16 v[32:47], v[10:13], v[2:5], v[32:47]
	s_waitcnt lgkmcnt(0)
	v_mfma_f32_32x32x16_bf16 v[16:31], v[68:71], v[64:67], v[16:31]
	v_mfma_f32_32x32x16_bf16 v[32:47], v[72:75], v[64:67], v[32:47]
	s_branch .Lstc_done
; #define MFMA32(a, b, c) __builtin_amdgcn_mfma_f32_32x32x16_bf16((a), (b), (c), 0, 0, 0)
; DI unsigned pk2(float lo, float hi) { f32x2 v = {lo, hi}; bf16x2v b = __builtin_convertvector(v, bf16x2v); return __builtin_bit_cast(unsigned, b); }
; DI void hgrn_stageC(const Params& p, const int j_even, char* lds) {
;     ...
;       for (int ks = 0; ks < 8; ++ks) {
;         bf16x8 qb = *(const bf16x8*)(Q2 + t * QROW + ks * 32 + hh * 16);
; #pragma unroll
;         for (int st = 0; st < 2; ++st) {
;           if (st <= tt) {
;             bf16x8 a = *(const bf16x8*)(K2 + (st * 32 + r) * QROW + ks * 32 + hh * 16);
;             sc[st] = MFMA32(a, qb, sc[st]);
;           }
;         }
;       }
;       f32x16 acc;
; #pragma unroll
;       for (int i = 0; i < 16; ++i) acc[i] = 0.f;
; #pragma unroll
;       for (int st = 0; st < 2; ++st) {
;         if (st <= tt) {
; #pragma unroll
;           for (int i = 0; i < 16; ++i) { const int s = st * 32 + (i & 3) + 8 * (i >> 2) + 4 * hh; if (s > t) sc[st][i] = 0.f; }
; #pragma unroll
;           for (int s2 = 0; s2 < 2; ++s2) {
;             u32x4 pw = {pk2(sc[st][8 * s2], sc[st][8 * s2 + 1]), pk2(sc[st][8 * s2 + 2], sc[st][8 * s2 + 3]), pk2(sc[st][8 * s2 + 4], sc[st][8 * s2 + 5]), pk2(sc[st][8 * s2 + 6], sc[st][8 * s2 + 7])};
;             const bf16x8 pf = __builtin_bit_cast(bf16x8, pw);
;             const char* ip = IT + (vt * 32 + r) * LROW + (st * 32 + 16 * s2 + 4 * hh) * 2;
;             u32x2 lo = *(const u32x2*)ip, hi = *(const u32x2*)(ip + 16);
;             u32x4 aw = {lo[0], lo[1], hi[0], hi[1]};
;             acc = MFMA32(__builtin_bit_cast(bf16x8, aw), pf, acc);
.Lstc_lo:
	ds_read_b128 v[2:5], v179 offset:52224
	ds_read_b128 v[6:9], v180
	ds_read_b128 v[64:67], v179 offset:52256
	ds_read_b128 v[68:71], v180 offset:32
	s_waitcnt lgkmcnt(2)
	v_mfma_f32_32x32x16_bf16 v[16:31], v[6:9], v[2:5], 0
	ds_read_b128 v[2:5], v179 offset:52288
	ds_read_b128 v[6:9], v180 offset:64
	s_waitcnt lgkmcnt(2)
	v_mfma_f32_32x32x16_bf16 v[16:31], v[68:71], v[64:67], v[16:31]
	ds_read_b128 v[64:67], v179 offset:52320
	ds_read_b128 v[68:71], v180 offset:96
	s_waitcnt lgkmcnt(2)
	v_mfma_f32_32x32x16_bf16 v[16:31], v[6:9], v[2:5], v[16:31]
	ds_read_b128 v[2:5], v179 offset:52352
	ds_read_b128 v[6:9], v180 offset:128
	s_waitcnt lgkmcnt(2)
	v_mfma_f32_32x32x16_bf16 v[16:31], v[68:71], v[64:67], v[16:31]
	ds_read_b128 v[64:67], v179 offset:52384
	ds_read_b128 v[68:71], v180 offset:160
	s_waitcnt lgkmcnt(2)
	v_mfma_f32_32x32x16_bf16 v[16:31], v[6:9], v[2:5], v[16:31]
	ds_read_b128 v[2:5], v179 offset:52416
	ds_read_b128 v[6:9], v180 offset:192
	s_waitcnt lgkmcnt(2)
	v_mfma_f32_32x32x16_bf16 v[16:31], v[68:71], v[64:67], v[16:31]
	ds_read_b128 v[64:67], v179 offset:52448
	ds_read_b128 v[68:71], v180 offset:224
	s_waitcnt lgkmcnt(2)
	v_mfma_f32_32x32x16_bf16 v[16:31], v[6:9], v[2:5], v[16:31]
	s_waitcnt lgkmcnt(0)
	v_mfma_f32_32x32x16_bf16 v[16:31], v[68:71], v[64:67], v[16:31]
.Lstc_done:
	s_nop 11
.LBB0_613:
	s_or_b64 exec, exec, vcc
	s_waitcnt lgkmcnt(0)
	s_and_saveexec_b64 vcc, s[14:15]
	s_cbranch_execz .LBB0_615
	v_readlane_b32 s30, v254, 54
	v_readlane_b32 s31, v254, 55
	ds_read2_b64 v[2:5], v181 offset1:2
	v_cndmask_b32_e64 v12, v23, 0, s[34:35]
	v_cndmask_b32_e64 v0, v16, 0, s[30:31]
	v_readlane_b32 s30, v254, 56
	v_readlane_b32 s31, v254, 57
	v_cndmask_b32_e64 v14, v24, 0, s[36:37]
	v_cndmask_b32_e64 v15, v25, 0, s[38:39]
	v_cndmask_b32_e64 v6, v17, 0, s[30:31]
	v_readlane_b32 s30, v254, 58
	v_readlane_b32 s31, v254, 59
	v_cvt_pk_bf16_f32 v6, v0, v6
	v_cndmask_b32_e64 v16, v26, 0, s[40:41]
	v_cndmask_b32_e64 v7, v18, 0, s[30:31]
	v_readlane_b32 s30, v254, 60
	v_readlane_b32 s31, v254, 61
	v_cndmask_b32_e64 v17, v27, 0, s[42:43]
	v_cndmask_b32_e64 v18, v28, 0, s[44:45]
	v_cndmask_b32_e64 v8, v19, 0, s[30:31]
	v_readlane_b32 s30, v254, 62
	v_readlane_b32 s31, v254, 63
	v_cvt_pk_bf16_f32 v7, v7, v8
	v_cndmask_b32_e64 v0, v29, 0, s[46:47]
	v_cndmask_b32_e64 v9, v20, 0, s[30:31]
	v_readlane_b32 s30, v255, 0
	v_readlane_b32 s31, v255, 1
	s_nop 1
	v_cndmask_b32_e64 v10, v21, 0, s[30:31]
	v_readlane_b32 s30, v255, 2
	v_readlane_b32 s31, v255, 3
	v_cvt_pk_bf16_f32 v8, v9, v10
	s_nop 0
	v_cndmask_b32_e64 v11, v22, 0, s[30:31]
	v_cvt_pk_bf16_f32 v9, v11, v12
	ds_read2_b64 v[10:13], v181 offset0:4 offset1:6
	s_waitcnt lgkmcnt(1)
	v_mfma_f32_32x32x16_bf16 v[48:63], v[2:5], v[6:9], 0
	v_cndmask_b32_e64 v5, v30, 0, s[48:49]
	v_cndmask_b32_e64 v6, v31, 0, s[50:51]
	v_cvt_pk_bf16_f32 v2, v14, v15
	v_cvt_pk_bf16_f32 v3, v16, v17
	v_cvt_pk_bf16_f32 v4, v18, v0
	v_cvt_pk_bf16_f32 v5, v5, v6
	s_waitcnt lgkmcnt(0)
	s_nop 0
	v_mfma_f32_32x32x16_bf16 v[48:63], v[10:13], v[2:5], v[48:63]

; #define MFMA32(a, b, c) __builtin_amdgcn_mfma_f32_32x32x16_bf16((a), (b), (c), 0, 0, 0)
; DI float xsum32(float v) { const u32x2 r_ = __builtin_amdgcn_permlane32_swap(__float_as_uint(v), __float_as_uint(v), false, false); return __uint_as_float(r_[0]) + __uint_as_float(r_[1]); }
; DI void hgrn_stageC(const Params& p, const int j_even, char* lds) {
;     ...
; #pragma unroll
;       for (int ks = 0; ks < 8; ++ks) {
;         bf16x8 a = *(const bf16x8*)(ST + (vt * 32 + r) * QROW + ks * 32 + hh * 16);
;         bf16x8 qb = *(const bf16x8*)(Q1 + t * QROW + ks * 32 + hh * 16);
;         acc = MFMA32(a, qb, acc);
;       }
;       float ssq = 0.f;
; #pragma unroll
;       for (int i = 0; i < 16; ++i) ssq += acc[i] * acc[i];
;       ssq = xsum32(ssq);
;       if (hh == 0) part[vt * 64 + t] = ssq;
.LBB0_617:
	s_or_b64 exec, exec, vcc
	ds_read_b128 v[2:5], v178
	ds_read_b128 v[6:9], v179 offset:34816
	s_waitcnt lgkmcnt(0)
	v_mfma_f32_32x32x16_bf16 v[48:63], v[2:5], v[6:9], v[48:63]
	ds_read_b128 v[2:5], v178 offset:32
	ds_read_b128 v[6:9], v179 offset:34848
	s_waitcnt lgkmcnt(0)
	v_mfma_f32_32x32x16_bf16 v[48:63], v[2:5], v[6:9], v[48:63]
	ds_read_b128 v[2:5], v178 offset:64
	ds_read_b128 v[6:9], v179 offset:34880
	s_waitcnt lgkmcnt(0)
	v_mfma_f32_32x32x16_bf16 v[48:63], v[2:5], v[6:9], v[48:63]
	ds_read_b128 v[2:5], v178 offset:96
	ds_read_b128 v[6:9], v179 offset:34912
	s_waitcnt lgkmcnt(0)
	v_mfma_f32_32x32x16_bf16 v[48:63], v[2:5], v[6:9], v[48:63]
	ds_read_b128 v[2:5], v178 offset:128
	ds_read_b128 v[6:9], v179 offset:34944
	s_waitcnt lgkmcnt(0)
	v_mfma_f32_32x32x16_bf16 v[48:63], v[2:5], v[6:9], v[48:63]
	ds_read_b128 v[2:5], v178 offset:160
	ds_read_b128 v[6:9], v179 offset:34976
	s_waitcnt lgkmcnt(0)
	v_mfma_f32_32x32x16_bf16 v[48:63], v[2:5], v[6:9], v[48:63]
	ds_read_b128 v[2:5], v178 offset:192
	ds_read_b128 v[6:9], v179 offset:35008
	s_waitcnt lgkmcnt(0)
	v_mfma_f32_32x32x16_bf16 v[48:63], v[2:5], v[6:9], v[48:63]
	ds_read_b128 v[2:5], v178 offset:224
	ds_read_b128 v[6:9], v179 offset:35040
	s_waitcnt lgkmcnt(0)
	v_mfma_f32_32x32x16_bf16 v[48:63], v[2:5], v[6:9], v[48:63]
	s_nop 11
	v_mul_f32_e32 v0, v49, v49
	v_fmac_f32_e32 v0, v48, v48
	v_fmac_f32_e32 v0, v50, v50
	v_fmac_f32_e32 v0, v51, v51
	v_fmac_f32_e32 v0, v52, v52
	v_fmac_f32_e32 v0, v53, v53
	v_fmac_f32_e32 v0, v54, v54
	v_fmac_f32_e32 v0, v55, v55
	v_fmac_f32_e32 v0, v56, v56
	v_fmac_f32_e32 v0, v57, v57
	v_fmac_f32_e32 v0, v58, v58
	v_fmac_f32_e32 v0, v59, v59
	v_fmac_f32_e32 v0, v60, v60
	v_fmac_f32_e32 v0, v61, v61
	v_fmac_f32_e32 v0, v62, v62
	v_fmac_f32_e32 v0, v63, v63
	v_mov_b32_e32 v2, v0
	s_nop 1
	v_permlane32_swap_b32_e32 v0, v2
	s_and_saveexec_b64 vcc, s[12:13]
	s_cbranch_execz .LBB0_592
	v_add_f32_e32 v0, v0, v2
	ds_write_b32 v168, v0
	s_branch .LBB0_592
.LBB0_633:
	v_readlane_b32 s74, v254, 30
	v_readlane_b32 s78, v254, 32
	v_readlane_b32 s80, v254, 34
	v_readlane_b32 s24, v254, 50
	v_readlane_b32 s6, v254, 48
	v_readlane_b32 s75, v254, 31
	v_readlane_b32 s79, v254, 33
	v_readlane_b32 s81, v254, 35
	v_readlane_b32 s48, v254, 36
	s_mov_b32 s49, 0xb0000
	s_mov_b32 s50, 0xfffff80
	v_readlane_b32 s51, v254, 37
	v_readlane_b32 s52, v254, 38
	s_movk_i32 s53, 0x3fdf
	s_mov_b32 s54, 0xbfb8aa3b
	s_mov_b32 s55, 0xb2a5705f
	s_mov_b32 s56, 0x42ce8ed0
	s_mov_b32 s57, 0xc2b17218
	s_mov_b32 s58, 0x7f800000
	s_mov_b32 s59, 0x3f2aaaab
	s_mov_b32 s60, 0x3f317218
	s_mov_b32 s61, 0x33800000
	s_brev_b32 s62, 48
	s_mov_b32 s63, 0x800000
	s_movk_i32 s64, 0x3fff
	s_mov_b32 s65, 0x10000
	s_movk_i32 s66, 0x100
	s_mov_b32 s67, 0x3a800000
	s_mov_b32 s68, 0x3f317217
	s_movk_i32 s69, 0x1600
	s_mov_b32 s70, 0x108000
	v_readlane_b32 s71, v254, 47
	v_readlane_b32 s26, v254, 52
	v_readlane_b32 s27, v254, 53
	v_readlane_b32 s7, v254, 49
	v_readlane_b32 s25, v254, 51
